# loop-edge rotation: both differential-attention tile loops close with one taken s_cbranch_scc1 into a one-instruction pre-header instead of cbranch + s_mov + s_branch
# speedup vs baseline: 1.0175x; 1.0033x over previous
.LBB0_255:
	s_sub_i32 s8, 4, s76
	v_lshlrev_b32_e32 v34, 1, v34
	v_cvt_f32_ubyte0_e32 v38, s8
	v_lshlrev_b32_e32 v158, 3, v33
	v_and_b32_e32 v34, 2, v34
	v_and_b32_e32 v37, 1, v37
	v_lshlrev_b32_e32 v33, 1, v33
	v_mul_f32_e32 v38, -2.0, v38
	v_bitop3_b32 v40, v34, v33, v37 bitop3:0x36
	v_or_b32_e32 v33, 1, v33
	v_exp_f32_e32 v38, v38
	v_and_b32_e32 v157, 63, v32
	v_bitop3_b32 v33, v34, v33, v37 bitop3:0x36
	v_cvt_f32_ubyte0_e32 v34, v35
	v_cvt_pk_bf16_f32 v34, v34, v34
	v_cmp_gt_u32_e32 vcc, 32, v157
	v_mul_f32_e32 v160, 0x3fb8aa3b, v38
	s_add_i32 s80, s75, 0xc000
	v_cndmask_b32_e32 v152, 0, v34, vcc
	v_or_b32_e32 v34, 32, v35
	v_cvt_f32_ubyte0_e32 v34, v34
	v_cvt_pk_bf16_f32 v34, v34, v34
	v_cndmask_b32_e32 v148, 0, v34, vcc
	v_cvt_pk_bf16_f32 v34, v160, 0
	v_lshlrev_b32_e32 v34, 16, v34
	v_fma_f32 v35, v38, s39, -v34
	v_cvt_pk_bf16_f32 v35, v35, 0
	v_lshlrev_b32_e32 v35, 16, v35
	v_cvt_pk_bf16_f32 v186, v34, v35
	v_xor_b32_e32 v34, 0x80000000, v34
	v_xor_b32_e32 v35, 0x80000000, v35
	v_cvt_pk_bf16_f32 v187, v34, v35
	v_or_b32_e32 v34, s5, v158
	v_sub_u32_e32 v35, v159, v34
	v_xad_u32 v34, v34, -1, v159
	v_cvt_f32_i32_e32 v34, v34
	v_add_u32_e32 v38, -2, v35
	v_add_u32_e32 v44, -3, v35
	v_cvt_f32_i32_e32 v37, v35
	v_cvt_f32_i32_e32 v38, v38
	v_cvt_f32_i32_e32 v44, v44
	v_fma_f32 v17, -v160, |v34|, v17
	v_add_u32_e32 v34, -4, v35
	v_cvt_f32_i32_e32 v34, v34
	v_fma_f32 v16, -v160, |v37|, v16
	v_fma_f32 v18, -v160, |v38|, v18
	v_fma_f32 v19, -v160, |v44|, v19
	v_add_u32_e32 v37, -5, v35
	v_add_u32_e32 v38, -6, v35
	v_add_u32_e32 v44, -7, v35
	v_cvt_f32_i32_e32 v37, v37
	v_cvt_f32_i32_e32 v38, v38
	v_cvt_f32_i32_e32 v44, v44
	v_fma_f32 v34, -v160, |v34|, v20
	v_add_u32_e32 v20, -16, v35
	v_cvt_f32_i32_e32 v20, v20
	v_fma_f32 v37, -v160, |v37|, v21
	v_fma_f32 v38, -v160, |v38|, v22
	v_fma_f32 v44, -v160, |v44|, v23
	v_subrev_u32_e32 v21, 17, v35
	v_subrev_u32_e32 v22, 18, v35
	v_subrev_u32_e32 v23, 19, v35
	v_cvt_f32_i32_e32 v21, v21
	v_cvt_f32_i32_e32 v22, v22
	v_cvt_f32_i32_e32 v23, v23
	v_fma_f32 v45, -v160, |v20|, v24
	v_subrev_u32_e32 v20, 20, v35
	v_cvt_f32_i32_e32 v20, v20
	v_fma_f32 v46, -v160, |v21|, v25
	v_fma_f32 v47, -v160, |v22|, v26
	v_fma_f32 v48, -v160, |v23|, v27
	v_subrev_u32_e32 v21, 21, v35
	v_subrev_u32_e32 v22, 22, v35
	v_subrev_u32_e32 v23, 23, v35
	v_cvt_f32_i32_e32 v21, v21
	v_cvt_f32_i32_e32 v22, v22
	v_cvt_f32_i32_e32 v23, v23
	v_fma_f32 v49, -v160, |v20|, v28
	v_subrev_u32_e32 v20, 32, v35
	v_cvt_f32_i32_e32 v20, v20
	v_fma_f32 v50, -v160, |v21|, v29
	v_fma_f32 v51, -v160, |v22|, v30
	v_fma_f32 v52, -v160, |v23|, v31
	v_subrev_u32_e32 v21, 33, v35
	v_subrev_u32_e32 v22, 34, v35
	v_subrev_u32_e32 v23, 35, v35
	v_cvt_f32_i32_e32 v21, v21
	v_cvt_f32_i32_e32 v22, v22
	v_cvt_f32_i32_e32 v23, v23
	v_fma_f32 v53, -v160, |v20|, v0
	v_subrev_u32_e32 v0, 36, v35
	v_cvt_f32_i32_e32 v0, v0
	v_fma_f32 v54, -v160, |v21|, v1
	v_fma_f32 v120, -v160, |v22|, v2
	v_fma_f32 v121, -v160, |v23|, v3
	v_subrev_u32_e32 v1, 37, v35
	v_subrev_u32_e32 v2, 38, v35
	v_subrev_u32_e32 v3, 39, v35
	v_cvt_f32_i32_e32 v1, v1
	v_cvt_f32_i32_e32 v2, v2
	v_cvt_f32_i32_e32 v3, v3
	v_fma_f32 v122, -v160, |v0|, v4
	v_subrev_u32_e32 v0, 48, v35
	v_cvt_f32_i32_e32 v0, v0
	v_fma_f32 v123, -v160, |v1|, v5
	v_fma_f32 v124, -v160, |v2|, v6
	v_fma_f32 v125, -v160, |v3|, v7
	v_subrev_u32_e32 v1, 49, v35
	v_subrev_u32_e32 v2, 50, v35
	v_subrev_u32_e32 v3, 51, v35
	v_cvt_f32_i32_e32 v1, v1
	v_cvt_f32_i32_e32 v2, v2
	v_cvt_f32_i32_e32 v3, v3
	v_fma_f32 v128, -v160, |v0|, v8
	v_subrev_u32_e32 v0, 52, v35
	v_cvt_f32_i32_e32 v0, v0
	v_fma_f32 v129, -v160, |v1|, v9
	v_fma_f32 v130, -v160, |v2|, v10
	v_fma_f32 v192, -v160, |v3|, v11
	v_subrev_u32_e32 v1, 53, v35
	v_subrev_u32_e32 v2, 54, v35
	v_subrev_u32_e32 v3, 55, v35
	v_cvt_f32_i32_e32 v1, v1
	v_cvt_f32_i32_e32 v2, v2
	v_cvt_f32_i32_e32 v3, v3
	s_lshl_b32 s5, s4, 14
	v_fma_f32 v204, -v160, |v0|, v12
	v_add_u32_e32 v0, s5, v170
	s_mov_b32 s8, m0
	s_mov_b32 m0, s80
	s_nop 0
	global_load_lds_dwordx4 v0, s[6:7]
	s_mov_b32 m0, s8
	v_add_u32_e32 v0, s5, v169
	s_add_i32 s81, s75, 0xe000
	s_mov_b32 s5, m0
	s_mov_b32 m0, s81
	s_nop 0
	global_load_lds_dwordx4 v0, s[6:7]
	s_mov_b32 m0, s5
	v_exp_f32_e32 v35, v16
	v_fma_f32 v205, -v160, |v1|, v13
	v_fma_f32 v206, -v160, |v2|, v14
	v_fma_f32 v207, -v160, |v3|, v15
	ds_read_b128 v[0:3], v171 offset:32768
	ds_read_b128 v[4:7], v171 offset:36864
	ds_read_b128 v[8:11], v174 offset:32768
	ds_read_b128 v[12:15], v174 offset:36864
	v_exp_f32_e32 v55, v17
	v_exp_f32_e32 v56, v18
	v_exp_f32_e32 v57, v19
	v_add_f32_e32 v16, 0, v35
	v_lshrrev_b32_e32 v36, 2, v36
	v_add_f32_e32 v16, v55, v16
	v_or_b32_e32 v39, v158, v36
	v_lshlrev_b32_e32 v32, 3, v32
	v_lshlrev_b32_e32 v36, 6, v36
	v_cndmask_b32_e32 v154, 0, v196, vcc
	v_cndmask_b32_e32 v153, 0, v197, vcc
	v_add_f32_e32 v16, v56, v16
	s_mov_b32 s76, 2
	v_and_b32_e32 v32, 8, v32
	v_xor_b32_e32 v41, 64, v36
	v_xor_b32_e32 v42, 0x80, v36
	v_xor_b32_e32 v43, 0xc0, v36
	v_lshlrev_b32_e32 v33, 4, v33
	v_mov_b32_e32 v155, v131
	v_mov_b32_e32 v149, v153
	v_mov_b32_e32 v150, v154
	v_mov_b32_e32 v151, v131
	v_add_f32_e32 v58, v57, v16
	s_waitcnt lgkmcnt(3)
	v_mfma_f32_32x32x16_bf16 v[80:95], v[0:3], v[144:147], 0
	ds_read_b128 v[16:19], v172 offset:32768
	ds_read_b128 v[20:23], v172 offset:36864
	ds_read_b128 v[24:27], v173 offset:32768
	ds_read_b128 v[28:31], v173 offset:36864
	v_exp_f32_e32 v34, v34
	v_exp_f32_e32 v37, v37
	v_add_f32_e32 v0, v34, v58
	v_add_f32_e32 v2, v37, v0
	s_waitcnt lgkmcnt(6)
	v_mfma_f32_32x32x16_bf16 v[64:79], v[4:7], v[144:147], 0
	v_exp_f32_e32 v3, v38
	v_exp_f32_e32 v38, v44
	v_cvt_pk_bf16_f32 v0, v35, v55
	v_cvt_pk_bf16_f32 v1, v56, v57
	v_add_f32_e32 v2, v3, v2
	v_add_f32_e32 v35, v38, v2
	v_cvt_pk_bf16_f32 v2, v34, v37
	v_cvt_pk_bf16_f32 v3, v3, v38
	s_waitcnt lgkmcnt(5)
	v_mfma_f32_32x32x16_bf16 v[80:95], v[8:11], v[140:143], v[80:95]
	v_exp_f32_e32 v34, v45
	v_exp_f32_e32 v37, v46
	v_add_f32_e32 v4, v34, v35
	v_add_f32_e32 v4, v37, v4
	s_waitcnt lgkmcnt(4)
	v_mfma_f32_32x32x16_bf16 v[64:79], v[12:15], v[140:143], v[64:79]
	v_exp_f32_e32 v35, v47
	v_exp_f32_e32 v38, v48
	v_add_f32_e32 v4, v35, v4
	v_add_f32_e32 v44, v38, v4
	v_lshl_or_b32 v4, v39, 8, v32
	v_lshl_or_b32 v12, v40, 4, v4
	v_or_b32_e32 v165, v12, v36
	v_add_u32_e32 v13, 0x400, v4
	v_or_b32_e32 v161, v12, v42
	v_add_u32_e32 v175, 0, v165
	v_or3_b32 v166, v33, v36, v13
	v_or_b32_e32 v167, v12, v41
	v_or3_b32 v168, v33, v41, v13
	v_add_u32_e32 v179, 0, v161
	v_or3_b32 v162, v33, v42, v13
	v_or_b32_e32 v163, v12, v43
	v_or3_b32 v164, v33, v43, v13
	s_waitcnt lgkmcnt(3)
	v_mfma_f32_32x32x16_bf16 v[80:95], v[16:19], v[136:139], v[80:95]
	v_add_u32_e32 v176, 0, v166
	v_add_u32_e32 v177, 0, v167
	v_add_u32_e32 v178, 0, v168
	ds_read_b64_tr_b16 v[4:5], v175 offset:16384
	ds_read_b64_tr_b16 v[6:7], v176 offset:16384
	ds_read_b64_tr_b16 v[8:9], v177 offset:16384
	ds_read_b64_tr_b16 v[10:11], v178 offset:16384
	v_add_u32_e32 v182, 0, v162
	v_add_u32_e32 v183, 0, v163
	v_add_u32_e32 v184, 0, v164
	ds_read_b64_tr_b16 v[12:13], v179 offset:16384
	ds_read_b64_tr_b16 v[14:15], v182 offset:16384
	ds_read_b64_tr_b16 v[96:97], v183 offset:16384
	ds_read_b64_tr_b16 v[98:99], v184 offset:16384
	v_exp_f32_e32 v32, v49
	v_exp_f32_e32 v33, v50
	v_add_f32_e32 v16, v32, v44
	v_add_f32_e32 v16, v33, v16
	s_waitcnt lgkmcnt(10)
	v_mfma_f32_32x32x16_bf16 v[64:79], v[20:23], v[136:139], v[64:79]
	v_exp_f32_e32 v17, v51
	v_exp_f32_e32 v18, v52
	v_cvt_pk_bf16_f32 v100, v34, v37
	v_cvt_pk_bf16_f32 v101, v35, v38
	v_add_f32_e32 v16, v17, v16
	v_add_f32_e32 v16, v18, v16
	v_cvt_pk_bf16_f32 v102, v32, v33
	v_cvt_pk_bf16_f32 v103, v17, v18
	s_waitcnt lgkmcnt(9)
	v_mfma_f32_32x32x16_bf16 v[80:95], v[24:27], v[132:135], v[80:95]
	s_waitcnt lgkmcnt(8)
	v_mfma_f32_32x32x16_bf16 v[64:79], v[28:31], v[132:135], v[64:79]
	ds_read_b64_tr_b16 v[104:105], v175 offset:20480
	ds_read_b64_tr_b16 v[106:107], v176 offset:20480
	ds_read_b64_tr_b16 v[108:109], v177 offset:20480
	ds_read_b64_tr_b16 v[110:111], v178 offset:20480
	ds_read_b64_tr_b16 v[112:113], v179 offset:20480
	ds_read_b64_tr_b16 v[114:115], v182 offset:20480
	ds_read_b64_tr_b16 v[116:117], v183 offset:20480
	ds_read_b64_tr_b16 v[118:119], v184 offset:20480
	v_exp_f32_e32 v126, v53
	v_exp_f32_e32 v127, v54
	s_waitcnt lgkmcnt(14)
	v_mfma_f32_32x32x16_bf16 v[48:63], v[4:7], v[0:3], 0
	v_lshl_or_b32 v17, s4, 6, v158
	v_add_f32_e32 v4, v126, v16
	v_add_f32_e32 v4, v127, v4
	v_sub_u32_e32 v208, v159, v17
	v_add_u32_e32 v209, -1, v208
	s_waitcnt lgkmcnt(12)
	v_mfma_f32_32x32x16_bf16 v[32:47], v[8:11], v[0:3], 0
	v_exp_f32_e32 v5, v120
	v_exp_f32_e32 v6, v121
	v_add_u32_e32 v210, -3, v208
	v_add_u32_e32 v211, -2, v208
	v_add_f32_e32 v4, v5, v4
	v_add_f32_e32 v4, v6, v4
	s_waitcnt lgkmcnt(10)
	v_mfma_f32_32x32x16_bf16 v[16:31], v[12:15], v[0:3], 0
	v_exp_f32_e32 v122, v122
	v_exp_f32_e32 v123, v123
	v_add_u32_e32 v212, -5, v208
	v_add_u32_e32 v213, -4, v208
	v_add_f32_e32 v4, v122, v4
	v_add_f32_e32 v4, v123, v4
	v_exp_f32_e32 v124, v124
	v_exp_f32_e32 v125, v125
	v_cvt_pk_bf16_f32 v121, v5, v6
	v_cvt_pk_bf16_f32 v120, v126, v127
	v_add_f32_e32 v4, v124, v4
	v_add_f32_e32 v214, v125, v4
	s_waitcnt lgkmcnt(8)
	v_mfma_f32_32x32x16_bf16 v[0:15], v[96:99], v[0:3], 0
	v_cvt_pk_bf16_f32 v122, v122, v123
	v_cvt_pk_bf16_f32 v123, v124, v125
	v_add_u32_e32 v215, -7, v208
	v_add_u32_e32 v216, -6, v208
	ds_read_b64_tr_b16 v[96:97], v175 offset:24576
	ds_read_b64_tr_b16 v[98:99], v176 offset:24576
	ds_read_b64_tr_b16 v[124:125], v177 offset:24576
	ds_read_b64_tr_b16 v[126:127], v178 offset:24576
	ds_read_b64_tr_b16 v[188:189], v179 offset:24576
	ds_read_b64_tr_b16 v[190:191], v182 offset:24576
	ds_read_b64_tr_b16 v[200:201], v183 offset:24576
	ds_read_b64_tr_b16 v[202:203], v184 offset:24576
	s_waitcnt lgkmcnt(14)
	v_mfma_f32_32x32x16_bf16 v[48:63], v[104:107], v[100:103], v[48:63]
	v_exp_f32_e32 v128, v128
	v_subrev_u32_e32 v105, 17, v208
	v_add_u32_e32 v106, -16, v208
	v_add_f32_e32 v104, v128, v214
	s_waitcnt lgkmcnt(12)
	v_mfma_f32_32x32x16_bf16 v[32:47], v[108:111], v[100:103], v[32:47]
	v_exp_f32_e32 v129, v129
	v_subrev_u32_e32 v107, 19, v208
	v_subrev_u32_e32 v214, 18, v208
	v_add_f32_e32 v104, v129, v104
	s_waitcnt lgkmcnt(10)
	v_mfma_f32_32x32x16_bf16 v[16:31], v[112:115], v[100:103], v[16:31]
	v_exp_f32_e32 v130, v130
	v_subrev_u32_e32 v108, 21, v208
	v_subrev_u32_e32 v109, 20, v208
	v_add_f32_e32 v104, v130, v104
	v_exp_f32_e32 v192, v192
	s_waitcnt lgkmcnt(8)
	v_mfma_f32_32x32x16_bf16 v[0:15], v[116:119], v[100:103], v[0:15]
	v_subrev_u32_e32 v110, 23, v208
	v_subrev_u32_e32 v111, 22, v208
	v_cvt_f32_i32_e32 v114, v111
	v_add_f32_e32 v217, v192, v104
	v_cvt_f32_i32_e32 v115, v110
	v_cvt_f32_i32_e32 v112, v109
	v_cvt_f32_i32_e32 v113, v108
	v_cvt_f32_i32_e32 v110, v214
	v_cvt_f32_i32_e32 v111, v107
	v_cvt_f32_i32_e32 v108, v106
	v_cvt_f32_i32_e32 v109, v105
	v_cvt_f32_i32_e32 v106, v216
	v_cvt_f32_i32_e32 v107, v215
	v_cvt_f32_i32_e32 v104, v213
	v_cvt_f32_i32_e32 v105, v212
	v_cvt_f32_i32_e32 v100, v208
	v_cvt_f32_i32_e32 v101, v209
	v_cvt_f32_i32_e32 v102, v210
	v_cvt_f32_i32_e32 v116, v211
	v_and_b32_e32 v100, 0x7fffffff, v100
	v_and_b32_e32 v101, 0x7fffffff, v101
	v_and_b32_e32 v103, 0x7fffffff, v102
	v_and_b32_e32 v102, 0x7fffffff, v116
	v_and_b32_e32 v105, 0x7fffffff, v105
	v_and_b32_e32 v104, 0x7fffffff, v104
	v_and_b32_e32 v107, 0x7fffffff, v107
	v_and_b32_e32 v106, 0x7fffffff, v106
	v_and_b32_e32 v109, 0x7fffffff, v109
	v_and_b32_e32 v108, 0x7fffffff, v108
	v_and_b32_e32 v111, 0x7fffffff, v111
	v_and_b32_e32 v110, 0x7fffffff, v110
	v_and_b32_e32 v113, 0x7fffffff, v113
	v_and_b32_e32 v112, 0x7fffffff, v112
	v_and_b32_e32 v115, 0x7fffffff, v115
	v_and_b32_e32 v114, 0x7fffffff, v114
	v_pk_fma_f32 v[94:95], v[160:161], v[114:115], v[94:95] op_sel_hi:[0,1,1] neg_lo:[1,0,0] neg_hi:[1,0,0]
	v_pk_fma_f32 v[92:93], v[160:161], v[112:113], v[92:93] op_sel_hi:[0,1,1] neg_lo:[1,0,0] neg_hi:[1,0,0]
	v_pk_fma_f32 v[90:91], v[160:161], v[110:111], v[90:91] op_sel_hi:[0,1,1] neg_lo:[1,0,0] neg_hi:[1,0,0]
	v_pk_fma_f32 v[88:89], v[160:161], v[108:109], v[88:89] op_sel_hi:[0,1,1] neg_lo:[1,0,0] neg_hi:[1,0,0]
	v_pk_fma_f32 v[86:87], v[160:161], v[106:107], v[86:87] op_sel_hi:[0,1,1] neg_lo:[1,0,0] neg_hi:[1,0,0]
	v_pk_fma_f32 v[84:85], v[160:161], v[104:105], v[84:85] op_sel_hi:[0,1,1] neg_lo:[1,0,0] neg_hi:[1,0,0]
	v_pk_fma_f32 v[82:83], v[160:161], v[102:103], v[82:83] op_sel_hi:[0,1,1] neg_lo:[1,0,0] neg_hi:[1,0,0]
	v_pk_fma_f32 v[80:81], v[160:161], v[100:101], v[80:81] op_sel_hi:[0,1,1] neg_lo:[1,0,0] neg_hi:[1,0,0]
	ds_read_b64_tr_b16 v[100:101], v175 offset:28672
	ds_read_b64_tr_b16 v[102:103], v176 offset:28672
	ds_read_b64_tr_b16 v[104:105], v177 offset:28672
	ds_read_b64_tr_b16 v[106:107], v178 offset:28672
	ds_read_b64_tr_b16 v[108:109], v179 offset:28672
	ds_read_b64_tr_b16 v[110:111], v182 offset:28672
	ds_read_b64_tr_b16 v[112:113], v183 offset:28672
	ds_read_b64_tr_b16 v[114:115], v184 offset:28672
	s_waitcnt lgkmcnt(14)
	v_mfma_f32_32x32x16_bf16 v[48:63], v[96:99], v[120:123], v[48:63]
	v_exp_f32_e32 v116, v204
	s_nop 0
	v_add_f32_e32 v96, v116, v217
	s_waitcnt lgkmcnt(12)
	v_mfma_f32_32x32x16_bf16 v[32:47], v[124:127], v[120:123], v[32:47]
	v_exp_f32_e32 v98, v205
	s_nop 0
	v_add_f32_e32 v96, v98, v96
	s_waitcnt lgkmcnt(10)
	v_mfma_f32_32x32x16_bf16 v[16:31], v[188:191], v[120:123], v[16:31]
	v_exp_f32_e32 v99, v206
	s_nop 0
	v_add_f32_e32 v117, v99, v96
	s_waitcnt lgkmcnt(8)
	v_mfma_f32_32x32x16_bf16 v[0:15], v[200:203], v[120:123], v[0:15]
	v_exp_f32_e32 v118, v207
	v_cvt_pk_bf16_f32 v96, v128, v129
	v_cvt_pk_bf16_f32 v97, v130, v192
	v_cvt_pk_bf16_f32 v98, v116, v98
	v_add_f32_e32 v116, v118, v117
	v_cvt_pk_bf16_f32 v99, v99, v118
	s_waitcnt lgkmcnt(6)
	s_nop 0
	v_mfma_f32_32x32x16_bf16 v[48:63], v[100:103], v[96:99], v[48:63]
	s_waitcnt lgkmcnt(4)
	v_mfma_f32_32x32x16_bf16 v[32:47], v[104:107], v[96:99], v[32:47]
	s_waitcnt lgkmcnt(2)
	v_mfma_f32_32x32x16_bf16 v[16:31], v[108:111], v[96:99], v[16:31]
	s_waitcnt lgkmcnt(0)
	v_mfma_f32_32x32x16_bf16 v[0:15], v[112:115], v[96:99], v[0:15]
	v_subrev_u32_e32 v100, 33, v208
	v_subrev_u32_e32 v101, 32, v208
	v_subrev_u32_e32 v102, 35, v208
	v_subrev_u32_e32 v103, 34, v208
	v_subrev_u32_e32 v104, 37, v208
	v_subrev_u32_e32 v105, 36, v208
	v_subrev_u32_e32 v96, 39, v208
	v_subrev_u32_e32 v97, 38, v208
	v_subrev_u32_e32 v98, 49, v208
	v_subrev_u32_e32 v99, 48, v208
	v_subrev_u32_e32 v106, 51, v208
	v_subrev_u32_e32 v107, 50, v208
	v_subrev_u32_e32 v108, 53, v208
	v_subrev_u32_e32 v109, 52, v208
	v_subrev_u32_e32 v110, 55, v208
	v_subrev_u32_e32 v111, 54, v208
	v_cvt_f32_i32_e32 v112, v111
	v_cvt_f32_i32_e32 v110, v110
	v_cvt_f32_i32_e32 v111, v109
	v_cvt_f32_i32_e32 v108, v108
	v_cvt_f32_i32_e32 v109, v107
	v_cvt_f32_i32_e32 v106, v106
	v_cvt_f32_i32_e32 v107, v99
	v_cvt_f32_i32_e32 v113, v98
	v_cvt_f32_i32_e32 v114, v97
	v_cvt_f32_i32_e32 v115, v96
	v_cvt_f32_i32_e32 v105, v105
	v_cvt_f32_i32_e32 v104, v104
	v_cvt_f32_i32_e32 v96, v100
	v_cvt_f32_i32_e32 v98, v101
	v_cvt_f32_i32_e32 v99, v102
	v_cvt_f32_i32_e32 v100, v103
	v_and_b32_e32 v97, 0x7fffffff, v96
	v_and_b32_e32 v96, 0x7fffffff, v98
	v_and_b32_e32 v99, 0x7fffffff, v99
	v_and_b32_e32 v98, 0x7fffffff, v100
	v_and_b32_e32 v101, 0x7fffffff, v104
	v_and_b32_e32 v100, 0x7fffffff, v105
	v_and_b32_e32 v103, 0x7fffffff, v115
	v_and_b32_e32 v102, 0x7fffffff, v114
	v_and_b32_e32 v105, 0x7fffffff, v113
	v_and_b32_e32 v104, 0x7fffffff, v107
	v_and_b32_e32 v107, 0x7fffffff, v106
	v_and_b32_e32 v106, 0x7fffffff, v109
	v_and_b32_e32 v109, 0x7fffffff, v108
	v_and_b32_e32 v108, 0x7fffffff, v111
	v_and_b32_e32 v111, 0x7fffffff, v110
	v_and_b32_e32 v110, 0x7fffffff, v112
	v_pk_fma_f32 v[78:79], v[160:161], v[110:111], v[78:79] op_sel_hi:[0,1,1] neg_lo:[1,0,0] neg_hi:[1,0,0]
	v_pk_fma_f32 v[76:77], v[160:161], v[108:109], v[76:77] op_sel_hi:[0,1,1] neg_lo:[1,0,0] neg_hi:[1,0,0]
	v_pk_fma_f32 v[74:75], v[160:161], v[106:107], v[74:75] op_sel_hi:[0,1,1] neg_lo:[1,0,0] neg_hi:[1,0,0]
	v_pk_fma_f32 v[72:73], v[160:161], v[104:105], v[72:73] op_sel_hi:[0,1,1] neg_lo:[1,0,0] neg_hi:[1,0,0]
	v_pk_fma_f32 v[70:71], v[160:161], v[102:103], v[70:71] op_sel_hi:[0,1,1] neg_lo:[1,0,0] neg_hi:[1,0,0]
	v_pk_fma_f32 v[68:69], v[160:161], v[100:101], v[68:69] op_sel_hi:[0,1,1] neg_lo:[1,0,0] neg_hi:[1,0,0]
	v_pk_fma_f32 v[66:67], v[160:161], v[98:99], v[66:67] op_sel_hi:[0,1,1] neg_lo:[1,0,0] neg_hi:[1,0,0]
	v_pk_fma_f32 v[64:65], v[160:161], v[96:97], v[64:65] op_sel_hi:[0,1,1] neg_lo:[1,0,0] neg_hi:[1,0,0]
	s_waitcnt vmcnt(0) lgkmcnt(0)
	s_barrier
	v_add_f32_e32 v188, 0, v116
	s_cmp_lt_i32 s70, 4
	s_cbranch_scc1 .LBB0_261
	s_mov_b32 s4, 4
.Lrot257:
	s_mov_b32 s76, s4

.LBB0_259:
	v_add_f32_e32 v80, 0, v80
	v_add_f32_e32 v80, v81, v80
	v_add_f32_e32 v80, v82, v80
	v_add_f32_e32 v80, v83, v80
	v_add_f32_e32 v80, v84, v80
	v_add_f32_e32 v80, v85, v80
	v_add_f32_e32 v80, v86, v80
	v_add_f32_e32 v80, v87, v80
	v_add_f32_e32 v80, v88, v80
	v_add_f32_e32 v80, v89, v80
	v_add_f32_e32 v80, v90, v80
	v_add_f32_e32 v80, v91, v80
	v_add_f32_e32 v80, v92, v80
	v_add_f32_e32 v80, v93, v80
	v_add_f32_e32 v80, v94, v80
	v_add_f32_e32 v80, v95, v80
	v_add_f32_e32 v64, v64, v80
	v_add_f32_e32 v64, v65, v64
	v_add_f32_e32 v64, v66, v64
	v_add_f32_e32 v64, v67, v64
	v_add_f32_e32 v64, v68, v64
	v_add_f32_e32 v64, v69, v64
	v_add_f32_e32 v64, v70, v64
	v_add_f32_e32 v64, v71, v64
	v_add_f32_e32 v64, v72, v64
	v_add_f32_e32 v64, v73, v64
	v_add_f32_e32 v64, v74, v64
	v_add_f32_e32 v64, v75, v64
	v_add_f32_e32 v64, v76, v64
	v_add_f32_e32 v64, v77, v64
	v_add_f32_e32 v64, v78, v64
	v_add_f32_e32 v64, v79, v64
	s_lshl_b32 s4, s82, 14
	v_add_f32_e32 v192, v188, v64
	v_add_u32_e32 v64, s4, v170
	s_mov_b32 s5, m0
	s_mov_b32 m0, s80
	s_nop 0
	global_load_lds_dwordx4 v64, s[6:7]
	s_mov_b32 m0, s5
	v_add_u32_e32 v64, s4, v169
	s_mov_b32 s4, m0
	s_mov_b32 m0, s81
	s_nop 0
	global_load_lds_dwordx4 v64, s[6:7]
	s_mov_b32 m0, s4
	s_lshl_b32 s4, s82, 6
	s_cmp_lt_i32 s82, s71
	v_subrev_u32_e32 v64, s4, v159
	v_sub_u32_e32 v65, 0, v64
	s_cselect_b64 s[4:5], -1, 0
	v_cndmask_b32_e64 v64, v65, v64, s[4:5]
	v_cvt_f32_i32_e32 v64, v64
	v_cndmask_b32_e64 v67, v187, v186, s[4:5]
	v_cndmask_b32_e32 v128, 0, v67, vcc
	ds_read_b128 v[188:191], v171 offset:32768
	ds_read_b128 v[200:203], v171 offset:36864
	ds_read_b128 v[204:207], v174 offset:32768
	ds_read_b128 v[208:211], v174 offset:36864
	v_mul_f32_e64 v65, -v160, v64
	v_cvt_pk_bf16_f32 v65, v65, 0
	v_lshlrev_b32_e32 v65, 16, v65
	v_fma_f32 v64, -v160, v64, -v65
	v_cvt_pk_bf16_f32 v66, v64, 0
	v_lshlrev_b32_e32 v66, 16, v66
	v_sub_f32_e32 v64, v64, v66
	v_cvt_pk_bf16_f32 v65, v65, v66
	v_cvt_pk_bf16_f32 v64, v64, 0
	v_cndmask_b32_e32 v129, 0, v65, vcc
	v_cndmask_b32_e32 v130, 0, v64, vcc
	v_exp_f32_e32 v224, v112
	v_exp_f32_e32 v225, v113
	v_mfma_f32_32x32x16_bf16 v[80:95], v[152:155], v[128:131], 0
	v_add_f32_e32 v64, 0, v224
	v_add_f32_e32 v64, v225, v64
	v_exp_f32_e32 v226, v114
	v_exp_f32_e32 v227, v115
	v_add_f32_e32 v64, v226, v64
	v_add_f32_e32 v228, v227, v64
	v_mfma_f32_32x32x16_bf16 v[64:79], v[148:151], v[128:131], 0
	s_waitcnt lgkmcnt(3)
	v_mfma_f32_32x32x16_bf16 v[80:95], v[188:191], v[144:147], v[80:95]
	ds_read_b128 v[112:115], v172 offset:32768
	ds_read_b128 v[212:215], v172 offset:36864
	ds_read_b128 v[216:219], v173 offset:32768
	ds_read_b128 v[220:223], v173 offset:36864
	v_exp_f32_e32 v128, v116
	v_exp_f32_e32 v129, v117
	v_add_f32_e32 v116, v128, v228
	v_add_f32_e32 v130, v129, v116
	s_waitcnt lgkmcnt(6)
	v_mfma_f32_32x32x16_bf16 v[64:79], v[200:203], v[144:147], v[64:79]
	v_exp_f32_e32 v188, v118
	v_exp_f32_e32 v119, v119
	v_cvt_pk_bf16_f32 v116, v224, v225
	v_cvt_pk_bf16_f32 v117, v226, v227
	v_add_f32_e32 v118, v188, v130
	v_add_f32_e32 v130, v119, v118
	v_cvt_pk_bf16_f32 v118, v128, v129
	v_cvt_pk_bf16_f32 v119, v188, v119
	s_waitcnt lgkmcnt(5)
	v_mfma_f32_32x32x16_bf16 v[80:95], v[204:207], v[140:143], v[80:95]
	v_exp_f32_e32 v128, v120
	v_exp_f32_e32 v129, v121
	v_add_f32_e32 v120, v128, v130
	v_add_f32_e32 v120, v129, v120
	s_waitcnt lgkmcnt(4)
	v_mfma_f32_32x32x16_bf16 v[64:79], v[208:211], v[140:143], v[64:79]
	v_exp_f32_e32 v130, v122
	v_exp_f32_e32 v224, v123
	v_add_f32_e32 v120, v130, v120
	v_add_f32_e32 v225, v224, v120
	ds_read_b64_tr_b16 v[120:121], v175 offset:16384
	ds_read_b64_tr_b16 v[122:123], v176 offset:16384
	ds_read_b64_tr_b16 v[188:189], v177 offset:16384
	ds_read_b64_tr_b16 v[190:191], v178 offset:16384
	ds_read_b64_tr_b16 v[200:201], v179 offset:16384
	ds_read_b64_tr_b16 v[202:203], v182 offset:16384
	ds_read_b64_tr_b16 v[204:205], v183 offset:16384
	ds_read_b64_tr_b16 v[206:207], v184 offset:16384
	s_waitcnt lgkmcnt(11)
	v_mfma_f32_32x32x16_bf16 v[80:95], v[112:115], v[136:139], v[80:95]
	v_exp_f32_e32 v124, v124
	v_exp_f32_e32 v125, v125
	v_add_f32_e32 v112, v124, v225
	v_add_f32_e32 v114, v125, v112
	s_waitcnt lgkmcnt(10)
	v_mfma_f32_32x32x16_bf16 v[64:79], v[212:215], v[136:139], v[64:79]
	v_exp_f32_e32 v115, v126
	v_exp_f32_e32 v126, v127
	v_cvt_pk_bf16_f32 v112, v128, v129
	v_cvt_pk_bf16_f32 v113, v130, v224
	v_add_f32_e32 v114, v115, v114
	v_add_f32_e32 v128, v126, v114
	v_cvt_pk_bf16_f32 v114, v124, v125
	v_cvt_pk_bf16_f32 v115, v115, v126
	s_waitcnt lgkmcnt(9)
	v_mfma_f32_32x32x16_bf16 v[80:95], v[216:219], v[132:135], v[80:95]
	s_waitcnt lgkmcnt(8)
	v_mfma_f32_32x32x16_bf16 v[64:79], v[220:223], v[132:135], v[64:79]
	ds_read_b64_tr_b16 v[124:125], v175 offset:20480
	ds_read_b64_tr_b16 v[126:127], v176 offset:20480
	ds_read_b64_tr_b16 v[208:209], v177 offset:20480
	ds_read_b64_tr_b16 v[210:211], v178 offset:20480
	ds_read_b64_tr_b16 v[212:213], v179 offset:20480
	ds_read_b64_tr_b16 v[214:215], v182 offset:20480
	ds_read_b64_tr_b16 v[216:217], v183 offset:20480
	ds_read_b64_tr_b16 v[218:219], v184 offset:20480
	s_waitcnt lgkmcnt(14)
	v_mfma_f32_32x32x16_bf16 v[48:63], v[120:123], v[116:119], v[48:63]
	v_exp_f32_e32 v96, v96
	v_exp_f32_e32 v97, v97
	v_add_f32_e32 v120, v96, v128
	v_add_f32_e32 v120, v97, v120
	s_waitcnt lgkmcnt(12)
	v_mfma_f32_32x32x16_bf16 v[32:47], v[188:191], v[116:119], v[32:47]
	v_exp_f32_e32 v98, v98
	v_exp_f32_e32 v99, v99
	v_add_f32_e32 v120, v98, v120
	v_add_f32_e32 v120, v99, v120
	s_waitcnt lgkmcnt(10)
	v_mfma_f32_32x32x16_bf16 v[16:31], v[200:203], v[116:119], v[16:31]
	v_exp_f32_e32 v100, v100
	v_exp_f32_e32 v101, v101
	v_add_f32_e32 v120, v100, v120
	v_add_f32_e32 v120, v101, v120
	s_waitcnt lgkmcnt(8)
	v_mfma_f32_32x32x16_bf16 v[0:15], v[204:207], v[116:119], v[0:15]
	v_exp_f32_e32 v102, v102
	v_exp_f32_e32 v103, v103
	v_cvt_pk_bf16_f32 v96, v96, v97
	v_cvt_pk_bf16_f32 v97, v98, v99
	v_add_f32_e32 v98, v102, v120
	v_add_f32_e32 v128, v103, v98
	v_cvt_pk_bf16_f32 v98, v100, v101
	v_cvt_pk_bf16_f32 v99, v102, v103
	ds_read_b64_tr_b16 v[100:101], v175 offset:24576
	ds_read_b64_tr_b16 v[102:103], v176 offset:24576
	ds_read_b64_tr_b16 v[116:117], v177 offset:24576
	ds_read_b64_tr_b16 v[118:119], v178 offset:24576
	ds_read_b64_tr_b16 v[120:121], v179 offset:24576
	ds_read_b64_tr_b16 v[122:123], v182 offset:24576
	ds_read_b64_tr_b16 v[188:189], v183 offset:24576
	ds_read_b64_tr_b16 v[190:191], v184 offset:24576
	s_waitcnt lgkmcnt(14)
	v_mfma_f32_32x32x16_bf16 v[48:63], v[124:127], v[112:115], v[48:63]
	v_exp_f32_e32 v129, v104
	s_nop 0
	v_add_f32_e32 v104, v129, v128
	s_waitcnt lgkmcnt(12)
	v_mfma_f32_32x32x16_bf16 v[32:47], v[208:211], v[112:115], v[32:47]
	v_exp_f32_e32 v128, v105
	s_nop 0
	v_add_f32_e32 v104, v128, v104
	s_waitcnt lgkmcnt(10)
	v_mfma_f32_32x32x16_bf16 v[16:31], v[212:215], v[112:115], v[16:31]
	v_exp_f32_e32 v130, v106
	s_nop 0
	v_add_f32_e32 v104, v130, v104
	s_waitcnt lgkmcnt(8)
	v_mfma_f32_32x32x16_bf16 v[0:15], v[216:219], v[112:115], v[0:15]
	v_exp_f32_e32 v204, v107
	s_nop 0
	v_add_f32_e32 v205, v204, v104
	ds_read_b64_tr_b16 v[104:105], v175 offset:28672
	ds_read_b64_tr_b16 v[106:107], v176 offset:28672
	ds_read_b64_tr_b16 v[112:113], v177 offset:28672
	ds_read_b64_tr_b16 v[114:115], v178 offset:28672
	ds_read_b64_tr_b16 v[124:125], v179 offset:28672
	ds_read_b64_tr_b16 v[126:127], v182 offset:28672
	ds_read_b64_tr_b16 v[200:201], v183 offset:28672
	ds_read_b64_tr_b16 v[202:203], v184 offset:28672
	s_waitcnt lgkmcnt(14)
	v_mfma_f32_32x32x16_bf16 v[48:63], v[100:103], v[96:99], v[48:63]
	v_exp_f32_e32 v108, v108
	s_nop 0
	v_add_f32_e32 v100, v108, v205
	s_waitcnt lgkmcnt(12)
	v_mfma_f32_32x32x16_bf16 v[32:47], v[116:119], v[96:99], v[32:47]
	v_exp_f32_e32 v102, v109
	s_nop 0
	v_add_f32_e32 v100, v102, v100
	s_waitcnt lgkmcnt(10)
	v_mfma_f32_32x32x16_bf16 v[16:31], v[120:123], v[96:99], v[16:31]
	v_exp_f32_e32 v103, v110
	s_nop 0
	v_add_f32_e32 v109, v103, v100
	s_waitcnt lgkmcnt(8)
	v_mfma_f32_32x32x16_bf16 v[0:15], v[188:191], v[96:99], v[0:15]
	v_exp_f32_e32 v110, v111
	v_cvt_pk_bf16_f32 v100, v129, v128
	v_cvt_pk_bf16_f32 v101, v130, v204
	v_cvt_pk_bf16_f32 v102, v108, v102
	v_add_f32_e32 v108, v110, v109
	v_cvt_pk_bf16_f32 v103, v103, v110
	s_waitcnt lgkmcnt(6)
	s_nop 0
	v_mfma_f32_32x32x16_bf16 v[48:63], v[104:107], v[100:103], v[48:63]
	s_waitcnt lgkmcnt(4)
	v_mfma_f32_32x32x16_bf16 v[32:47], v[112:115], v[100:103], v[32:47]
	s_waitcnt lgkmcnt(2)
	v_mfma_f32_32x32x16_bf16 v[16:31], v[124:127], v[100:103], v[16:31]
	s_waitcnt lgkmcnt(0)
	v_mfma_f32_32x32x16_bf16 v[0:15], v[200:203], v[100:103], v[0:15]
	s_waitcnt vmcnt(0) lgkmcnt(0)
	s_barrier
	s_add_i32 s4, s76, 2
	s_add_i32 s5, s76, 1
	v_add_f32_e32 v188, v192, v108
	s_cmp_lt_i32 s5, s70
	s_cbranch_scc1 .Lrot257

.LBB0_299:
	s_sub_i32 s8, 4, s74
	v_cvt_f32_u32_e32 v38, s8
	v_lshlrev_b32_e32 v34, 1, v34
	v_lshlrev_b32_e32 v158, 3, v33
	v_and_b32_e32 v34, 2, v34
	v_and_b32_e32 v37, 1, v37
	v_lshlrev_b32_e32 v33, 1, v33
	v_mul_f32_e32 v38, -2.0, v38
	v_bitop3_b32 v40, v34, v33, v37 bitop3:0x36
	v_or_b32_e32 v33, 1, v33
	v_and_b32_e32 v157, 63, v32
	v_exp_f32_e32 v38, v38
	v_bitop3_b32 v33, v34, v33, v37 bitop3:0x36
	v_cvt_f32_ubyte0_e32 v34, v35
	v_cvt_pk_bf16_f32 v34, v34, v34
	v_cmp_gt_u32_e32 vcc, 32, v157
	v_mul_f32_e32 v160, 0x3fb8aa3b, v38
	s_add_i32 s78, s73, 0xc000
	v_cndmask_b32_e32 v152, 0, v34, vcc
	v_or_b32_e32 v34, 32, v35
	v_cvt_f32_ubyte0_e32 v34, v34
	v_cvt_pk_bf16_f32 v34, v34, v34
	v_cndmask_b32_e32 v148, 0, v34, vcc
	v_cvt_pk_bf16_f32 v34, v160, 0
	v_lshlrev_b32_e32 v34, 16, v34
	v_fma_f32 v35, v38, s39, -v34
	v_cvt_pk_bf16_f32 v35, v35, 0
	v_lshlrev_b32_e32 v35, 16, v35
	v_cvt_pk_bf16_f32 v186, v34, v35
	v_xor_b32_e32 v34, 0x80000000, v34
	v_xor_b32_e32 v35, 0x80000000, v35
	v_cvt_pk_bf16_f32 v187, v34, v35
	v_or_b32_e32 v34, s5, v158
	v_sub_u32_e32 v35, v159, v34
	v_xad_u32 v34, v34, -1, v159
	v_cvt_f32_i32_e32 v34, v34
	v_add_u32_e32 v38, -2, v35
	v_add_u32_e32 v44, -3, v35
	v_cvt_f32_i32_e32 v37, v35
	v_cvt_f32_i32_e32 v38, v38
	v_cvt_f32_i32_e32 v44, v44
	v_fma_f32 v17, -v160, |v34|, v17
	v_add_u32_e32 v34, -4, v35
	v_cvt_f32_i32_e32 v34, v34
	v_fma_f32 v16, -v160, |v37|, v16
	v_fma_f32 v18, -v160, |v38|, v18
	v_fma_f32 v19, -v160, |v44|, v19
	v_add_u32_e32 v37, -5, v35
	v_add_u32_e32 v38, -6, v35
	v_add_u32_e32 v44, -7, v35
	v_cvt_f32_i32_e32 v37, v37
	v_cvt_f32_i32_e32 v38, v38
	v_cvt_f32_i32_e32 v44, v44
	v_fma_f32 v34, -v160, |v34|, v20
	v_add_u32_e32 v20, -16, v35
	v_cvt_f32_i32_e32 v20, v20
	v_fma_f32 v37, -v160, |v37|, v21
	v_fma_f32 v38, -v160, |v38|, v22
	v_fma_f32 v44, -v160, |v44|, v23
	v_subrev_u32_e32 v21, 17, v35
	v_subrev_u32_e32 v22, 18, v35
	v_subrev_u32_e32 v23, 19, v35
	v_cvt_f32_i32_e32 v21, v21
	v_cvt_f32_i32_e32 v22, v22
	v_cvt_f32_i32_e32 v23, v23
	v_fma_f32 v45, -v160, |v20|, v24
	v_subrev_u32_e32 v20, 20, v35
	v_cvt_f32_i32_e32 v20, v20
	v_fma_f32 v46, -v160, |v21|, v25
	v_fma_f32 v47, -v160, |v22|, v26
	v_fma_f32 v48, -v160, |v23|, v27
	v_subrev_u32_e32 v21, 21, v35
	v_subrev_u32_e32 v22, 22, v35
	v_subrev_u32_e32 v23, 23, v35
	v_cvt_f32_i32_e32 v21, v21
	v_cvt_f32_i32_e32 v22, v22
	v_cvt_f32_i32_e32 v23, v23
	v_fma_f32 v49, -v160, |v20|, v28
	v_subrev_u32_e32 v20, 32, v35
	v_cvt_f32_i32_e32 v20, v20
	v_fma_f32 v50, -v160, |v21|, v29
	v_fma_f32 v51, -v160, |v22|, v30
	v_fma_f32 v52, -v160, |v23|, v31
	v_subrev_u32_e32 v21, 33, v35
	v_subrev_u32_e32 v22, 34, v35
	v_subrev_u32_e32 v23, 35, v35
	v_cvt_f32_i32_e32 v21, v21
	v_cvt_f32_i32_e32 v22, v22
	v_cvt_f32_i32_e32 v23, v23
	v_fma_f32 v53, -v160, |v20|, v0
	v_subrev_u32_e32 v0, 36, v35
	v_cvt_f32_i32_e32 v0, v0
	v_fma_f32 v54, -v160, |v21|, v1
	v_fma_f32 v120, -v160, |v22|, v2
	v_fma_f32 v121, -v160, |v23|, v3
	v_subrev_u32_e32 v1, 37, v35
	v_subrev_u32_e32 v2, 38, v35
	v_subrev_u32_e32 v3, 39, v35
	v_cvt_f32_i32_e32 v1, v1
	v_cvt_f32_i32_e32 v2, v2
	v_cvt_f32_i32_e32 v3, v3
	v_fma_f32 v122, -v160, |v0|, v4
	v_subrev_u32_e32 v0, 48, v35
	v_cvt_f32_i32_e32 v0, v0
	v_fma_f32 v123, -v160, |v1|, v5
	v_fma_f32 v124, -v160, |v2|, v6
	v_fma_f32 v125, -v160, |v3|, v7
	v_subrev_u32_e32 v1, 49, v35
	v_subrev_u32_e32 v2, 50, v35
	v_subrev_u32_e32 v3, 51, v35
	v_cvt_f32_i32_e32 v1, v1
	v_cvt_f32_i32_e32 v2, v2
	v_cvt_f32_i32_e32 v3, v3
	v_fma_f32 v128, -v160, |v0|, v8
	v_subrev_u32_e32 v0, 52, v35
	v_cvt_f32_i32_e32 v0, v0
	v_fma_f32 v129, -v160, |v1|, v9
	v_fma_f32 v130, -v160, |v2|, v10
	v_fma_f32 v192, -v160, |v3|, v11
	v_subrev_u32_e32 v1, 53, v35
	v_subrev_u32_e32 v2, 54, v35
	v_subrev_u32_e32 v3, 55, v35
	v_cvt_f32_i32_e32 v1, v1
	v_cvt_f32_i32_e32 v2, v2
	v_cvt_f32_i32_e32 v3, v3
	s_lshl_b32 s5, s4, 14
	v_fma_f32 v204, -v160, |v0|, v12
	v_add_u32_e32 v0, s5, v170
	s_mov_b32 s8, m0
	s_mov_b32 m0, s78
	s_nop 0
	global_load_lds_dwordx4 v0, s[6:7]
	s_mov_b32 m0, s8
	v_add_u32_e32 v0, s5, v169
	s_add_i32 s79, s73, 0xe000
	s_mov_b32 s5, m0
	s_mov_b32 m0, s79
	s_nop 0
	global_load_lds_dwordx4 v0, s[6:7]
	s_mov_b32 m0, s5
	v_exp_f32_e32 v35, v16
	v_fma_f32 v205, -v160, |v1|, v13
	v_fma_f32 v206, -v160, |v2|, v14
	v_fma_f32 v207, -v160, |v3|, v15
	ds_read_b128 v[0:3], v171 offset:32768
	ds_read_b128 v[4:7], v171 offset:36864
	ds_read_b128 v[8:11], v174 offset:32768
	ds_read_b128 v[12:15], v174 offset:36864
	v_exp_f32_e32 v55, v17
	v_exp_f32_e32 v56, v18
	v_exp_f32_e32 v57, v19
	v_add_f32_e32 v16, 0, v35
	v_lshrrev_b32_e32 v36, 2, v36
	v_add_f32_e32 v16, v55, v16
	v_or_b32_e32 v39, v158, v36
	v_lshlrev_b32_e32 v32, 3, v32
	v_lshlrev_b32_e32 v36, 6, v36
	v_cndmask_b32_e32 v154, 0, v196, vcc
	v_cndmask_b32_e32 v153, 0, v197, vcc
	v_add_f32_e32 v16, v56, v16
	s_mov_b32 s74, 2
	v_and_b32_e32 v32, 8, v32
	v_xor_b32_e32 v41, 64, v36
	v_xor_b32_e32 v42, 0x80, v36
	v_xor_b32_e32 v43, 0xc0, v36
	v_lshlrev_b32_e32 v33, 4, v33
	v_mov_b32_e32 v155, v131
	v_mov_b32_e32 v149, v153
	v_mov_b32_e32 v150, v154
	v_mov_b32_e32 v151, v131
	v_add_f32_e32 v58, v57, v16
	s_waitcnt lgkmcnt(3)
	v_mfma_f32_32x32x16_bf16 v[80:95], v[0:3], v[144:147], 0
	ds_read_b128 v[16:19], v172 offset:32768
	ds_read_b128 v[20:23], v172 offset:36864
	ds_read_b128 v[24:27], v173 offset:32768
	ds_read_b128 v[28:31], v173 offset:36864
	v_exp_f32_e32 v34, v34
	v_exp_f32_e32 v37, v37
	v_add_f32_e32 v0, v34, v58
	v_add_f32_e32 v2, v37, v0
	s_waitcnt lgkmcnt(6)
	v_mfma_f32_32x32x16_bf16 v[64:79], v[4:7], v[144:147], 0
	v_exp_f32_e32 v3, v38
	v_exp_f32_e32 v38, v44
	v_cvt_pk_bf16_f32 v0, v35, v55
	v_cvt_pk_bf16_f32 v1, v56, v57
	v_add_f32_e32 v2, v3, v2
	v_add_f32_e32 v35, v38, v2
	v_cvt_pk_bf16_f32 v2, v34, v37
	v_cvt_pk_bf16_f32 v3, v3, v38
	s_waitcnt lgkmcnt(5)
	v_mfma_f32_32x32x16_bf16 v[80:95], v[8:11], v[140:143], v[80:95]
	v_exp_f32_e32 v34, v45
	v_exp_f32_e32 v37, v46
	v_add_f32_e32 v4, v34, v35
	v_add_f32_e32 v4, v37, v4
	s_waitcnt lgkmcnt(4)
	v_mfma_f32_32x32x16_bf16 v[64:79], v[12:15], v[140:143], v[64:79]
	v_exp_f32_e32 v35, v47
	v_exp_f32_e32 v38, v48
	v_add_f32_e32 v4, v35, v4
	v_add_f32_e32 v44, v38, v4
	v_lshl_or_b32 v4, v39, 8, v32
	v_lshl_or_b32 v12, v40, 4, v4
	v_or_b32_e32 v165, v12, v36
	v_add_u32_e32 v13, 0x400, v4
	v_or_b32_e32 v161, v12, v42
	v_add_u32_e32 v175, 0, v165
	v_or3_b32 v166, v33, v36, v13
	v_or_b32_e32 v167, v12, v41
	v_or3_b32 v168, v33, v41, v13
	v_add_u32_e32 v179, 0, v161
	v_or3_b32 v162, v33, v42, v13
	v_or_b32_e32 v163, v12, v43
	v_or3_b32 v164, v33, v43, v13
	s_waitcnt lgkmcnt(3)
	v_mfma_f32_32x32x16_bf16 v[80:95], v[16:19], v[136:139], v[80:95]
	v_add_u32_e32 v176, 0, v166
	v_add_u32_e32 v177, 0, v167
	v_add_u32_e32 v178, 0, v168
	ds_read_b64_tr_b16 v[4:5], v175 offset:16384
	ds_read_b64_tr_b16 v[6:7], v176 offset:16384
	ds_read_b64_tr_b16 v[8:9], v177 offset:16384
	ds_read_b64_tr_b16 v[10:11], v178 offset:16384
	v_add_u32_e32 v182, 0, v162
	v_add_u32_e32 v183, 0, v163
	v_add_u32_e32 v184, 0, v164
	ds_read_b64_tr_b16 v[12:13], v179 offset:16384
	ds_read_b64_tr_b16 v[14:15], v182 offset:16384
	ds_read_b64_tr_b16 v[96:97], v183 offset:16384
	ds_read_b64_tr_b16 v[98:99], v184 offset:16384
	v_exp_f32_e32 v32, v49
	v_exp_f32_e32 v33, v50
	v_add_f32_e32 v16, v32, v44
	v_add_f32_e32 v16, v33, v16
	s_waitcnt lgkmcnt(10)
	v_mfma_f32_32x32x16_bf16 v[64:79], v[20:23], v[136:139], v[64:79]
	v_exp_f32_e32 v17, v51
	v_exp_f32_e32 v18, v52
	v_cvt_pk_bf16_f32 v100, v34, v37
	v_cvt_pk_bf16_f32 v101, v35, v38
	v_add_f32_e32 v16, v17, v16
	v_add_f32_e32 v16, v18, v16
	v_cvt_pk_bf16_f32 v102, v32, v33
	v_cvt_pk_bf16_f32 v103, v17, v18
	s_waitcnt lgkmcnt(9)
	v_mfma_f32_32x32x16_bf16 v[80:95], v[24:27], v[132:135], v[80:95]
	s_waitcnt lgkmcnt(8)
	v_mfma_f32_32x32x16_bf16 v[64:79], v[28:31], v[132:135], v[64:79]
	ds_read_b64_tr_b16 v[104:105], v175 offset:20480
	ds_read_b64_tr_b16 v[106:107], v176 offset:20480
	ds_read_b64_tr_b16 v[108:109], v177 offset:20480
	ds_read_b64_tr_b16 v[110:111], v178 offset:20480
	ds_read_b64_tr_b16 v[112:113], v179 offset:20480
	ds_read_b64_tr_b16 v[114:115], v182 offset:20480
	ds_read_b64_tr_b16 v[116:117], v183 offset:20480
	ds_read_b64_tr_b16 v[118:119], v184 offset:20480
	v_exp_f32_e32 v126, v53
	v_exp_f32_e32 v127, v54
	s_waitcnt lgkmcnt(14)
	v_mfma_f32_32x32x16_bf16 v[48:63], v[4:7], v[0:3], 0
	v_lshl_or_b32 v17, s4, 6, v158
	v_add_f32_e32 v4, v126, v16
	v_add_f32_e32 v4, v127, v4
	v_sub_u32_e32 v208, v159, v17
	v_add_u32_e32 v209, -1, v208
	s_waitcnt lgkmcnt(12)
	v_mfma_f32_32x32x16_bf16 v[32:47], v[8:11], v[0:3], 0
	v_exp_f32_e32 v5, v120
	v_exp_f32_e32 v6, v121
	v_add_u32_e32 v210, -3, v208
	v_add_u32_e32 v211, -2, v208
	v_add_f32_e32 v4, v5, v4
	v_add_f32_e32 v4, v6, v4
	s_waitcnt lgkmcnt(10)
	v_mfma_f32_32x32x16_bf16 v[16:31], v[12:15], v[0:3], 0
	v_exp_f32_e32 v122, v122
	v_exp_f32_e32 v123, v123
	v_add_u32_e32 v212, -5, v208
	v_add_u32_e32 v213, -4, v208
	v_add_f32_e32 v4, v122, v4
	v_add_f32_e32 v4, v123, v4
	v_exp_f32_e32 v124, v124
	v_exp_f32_e32 v125, v125
	v_cvt_pk_bf16_f32 v121, v5, v6
	v_cvt_pk_bf16_f32 v120, v126, v127
	v_add_f32_e32 v4, v124, v4
	v_add_f32_e32 v214, v125, v4
	s_waitcnt lgkmcnt(8)
	v_mfma_f32_32x32x16_bf16 v[0:15], v[96:99], v[0:3], 0
	v_cvt_pk_bf16_f32 v122, v122, v123
	v_cvt_pk_bf16_f32 v123, v124, v125
	v_add_u32_e32 v215, -7, v208
	v_add_u32_e32 v216, -6, v208
	ds_read_b64_tr_b16 v[96:97], v175 offset:24576
	ds_read_b64_tr_b16 v[98:99], v176 offset:24576
	ds_read_b64_tr_b16 v[124:125], v177 offset:24576
	ds_read_b64_tr_b16 v[126:127], v178 offset:24576
	ds_read_b64_tr_b16 v[188:189], v179 offset:24576
	ds_read_b64_tr_b16 v[190:191], v182 offset:24576
	ds_read_b64_tr_b16 v[200:201], v183 offset:24576
	ds_read_b64_tr_b16 v[202:203], v184 offset:24576
	s_waitcnt lgkmcnt(14)
	v_mfma_f32_32x32x16_bf16 v[48:63], v[104:107], v[100:103], v[48:63]
	v_exp_f32_e32 v128, v128
	v_subrev_u32_e32 v105, 17, v208
	v_add_u32_e32 v106, -16, v208
	v_add_f32_e32 v104, v128, v214
	s_waitcnt lgkmcnt(12)
	v_mfma_f32_32x32x16_bf16 v[32:47], v[108:111], v[100:103], v[32:47]
	v_exp_f32_e32 v129, v129
	v_subrev_u32_e32 v107, 19, v208
	v_subrev_u32_e32 v214, 18, v208
	v_add_f32_e32 v104, v129, v104
	s_waitcnt lgkmcnt(10)
	v_mfma_f32_32x32x16_bf16 v[16:31], v[112:115], v[100:103], v[16:31]
	v_exp_f32_e32 v130, v130
	v_subrev_u32_e32 v108, 21, v208
	v_subrev_u32_e32 v109, 20, v208
	v_add_f32_e32 v104, v130, v104
	v_exp_f32_e32 v192, v192
	s_waitcnt lgkmcnt(8)
	v_mfma_f32_32x32x16_bf16 v[0:15], v[116:119], v[100:103], v[0:15]
	v_subrev_u32_e32 v110, 23, v208
	v_subrev_u32_e32 v111, 22, v208
	v_cvt_f32_i32_e32 v114, v111
	v_add_f32_e32 v217, v192, v104
	v_cvt_f32_i32_e32 v115, v110
	v_cvt_f32_i32_e32 v112, v109
	v_cvt_f32_i32_e32 v113, v108
	v_cvt_f32_i32_e32 v110, v214
	v_cvt_f32_i32_e32 v111, v107
	v_cvt_f32_i32_e32 v108, v106
	v_cvt_f32_i32_e32 v109, v105
	v_cvt_f32_i32_e32 v106, v216
	v_cvt_f32_i32_e32 v107, v215
	v_cvt_f32_i32_e32 v104, v213
	v_cvt_f32_i32_e32 v105, v212
	v_cvt_f32_i32_e32 v100, v208
	v_cvt_f32_i32_e32 v101, v209
	v_cvt_f32_i32_e32 v102, v210
	v_cvt_f32_i32_e32 v116, v211
	v_and_b32_e32 v100, 0x7fffffff, v100
	v_and_b32_e32 v101, 0x7fffffff, v101
	v_and_b32_e32 v103, 0x7fffffff, v102
	v_and_b32_e32 v102, 0x7fffffff, v116
	v_and_b32_e32 v105, 0x7fffffff, v105
	v_and_b32_e32 v104, 0x7fffffff, v104
	v_and_b32_e32 v107, 0x7fffffff, v107
	v_and_b32_e32 v106, 0x7fffffff, v106
	v_and_b32_e32 v109, 0x7fffffff, v109
	v_and_b32_e32 v108, 0x7fffffff, v108
	v_and_b32_e32 v111, 0x7fffffff, v111
	v_and_b32_e32 v110, 0x7fffffff, v110
	v_and_b32_e32 v113, 0x7fffffff, v113
	v_and_b32_e32 v112, 0x7fffffff, v112
	v_and_b32_e32 v115, 0x7fffffff, v115
	v_and_b32_e32 v114, 0x7fffffff, v114
	v_pk_fma_f32 v[94:95], v[160:161], v[114:115], v[94:95] op_sel_hi:[0,1,1] neg_lo:[1,0,0] neg_hi:[1,0,0]
	v_pk_fma_f32 v[92:93], v[160:161], v[112:113], v[92:93] op_sel_hi:[0,1,1] neg_lo:[1,0,0] neg_hi:[1,0,0]
	v_pk_fma_f32 v[90:91], v[160:161], v[110:111], v[90:91] op_sel_hi:[0,1,1] neg_lo:[1,0,0] neg_hi:[1,0,0]
	v_pk_fma_f32 v[88:89], v[160:161], v[108:109], v[88:89] op_sel_hi:[0,1,1] neg_lo:[1,0,0] neg_hi:[1,0,0]
	v_pk_fma_f32 v[86:87], v[160:161], v[106:107], v[86:87] op_sel_hi:[0,1,1] neg_lo:[1,0,0] neg_hi:[1,0,0]
	v_pk_fma_f32 v[84:85], v[160:161], v[104:105], v[84:85] op_sel_hi:[0,1,1] neg_lo:[1,0,0] neg_hi:[1,0,0]
	v_pk_fma_f32 v[82:83], v[160:161], v[102:103], v[82:83] op_sel_hi:[0,1,1] neg_lo:[1,0,0] neg_hi:[1,0,0]
	v_pk_fma_f32 v[80:81], v[160:161], v[100:101], v[80:81] op_sel_hi:[0,1,1] neg_lo:[1,0,0] neg_hi:[1,0,0]
	ds_read_b64_tr_b16 v[100:101], v175 offset:28672
	ds_read_b64_tr_b16 v[102:103], v176 offset:28672
	ds_read_b64_tr_b16 v[104:105], v177 offset:28672
	ds_read_b64_tr_b16 v[106:107], v178 offset:28672
	ds_read_b64_tr_b16 v[108:109], v179 offset:28672
	ds_read_b64_tr_b16 v[110:111], v182 offset:28672
	ds_read_b64_tr_b16 v[112:113], v183 offset:28672
	ds_read_b64_tr_b16 v[114:115], v184 offset:28672
	s_waitcnt lgkmcnt(14)
	v_mfma_f32_32x32x16_bf16 v[48:63], v[96:99], v[120:123], v[48:63]
	v_exp_f32_e32 v116, v204
	s_nop 0
	v_add_f32_e32 v96, v116, v217
	s_waitcnt lgkmcnt(12)
	v_mfma_f32_32x32x16_bf16 v[32:47], v[124:127], v[120:123], v[32:47]
	v_exp_f32_e32 v98, v205
	s_nop 0
	v_add_f32_e32 v96, v98, v96
	s_waitcnt lgkmcnt(10)
	v_mfma_f32_32x32x16_bf16 v[16:31], v[188:191], v[120:123], v[16:31]
	v_exp_f32_e32 v99, v206
	s_nop 0
	v_add_f32_e32 v117, v99, v96
	s_waitcnt lgkmcnt(8)
	v_mfma_f32_32x32x16_bf16 v[0:15], v[200:203], v[120:123], v[0:15]
	v_exp_f32_e32 v118, v207
	v_cvt_pk_bf16_f32 v96, v128, v129
	v_cvt_pk_bf16_f32 v97, v130, v192
	v_cvt_pk_bf16_f32 v98, v116, v98
	v_add_f32_e32 v116, v118, v117
	v_cvt_pk_bf16_f32 v99, v99, v118
	s_waitcnt lgkmcnt(6)
	s_nop 0
	v_mfma_f32_32x32x16_bf16 v[48:63], v[100:103], v[96:99], v[48:63]
	s_waitcnt lgkmcnt(4)
	v_mfma_f32_32x32x16_bf16 v[32:47], v[104:107], v[96:99], v[32:47]
	s_waitcnt lgkmcnt(2)
	v_mfma_f32_32x32x16_bf16 v[16:31], v[108:111], v[96:99], v[16:31]
	s_waitcnt lgkmcnt(0)
	v_mfma_f32_32x32x16_bf16 v[0:15], v[112:115], v[96:99], v[0:15]
	v_subrev_u32_e32 v100, 33, v208
	v_subrev_u32_e32 v101, 32, v208
	v_subrev_u32_e32 v102, 35, v208
	v_subrev_u32_e32 v103, 34, v208
	v_subrev_u32_e32 v104, 37, v208
	v_subrev_u32_e32 v105, 36, v208
	v_subrev_u32_e32 v96, 39, v208
	v_subrev_u32_e32 v97, 38, v208
	v_subrev_u32_e32 v98, 49, v208
	v_subrev_u32_e32 v99, 48, v208
	v_subrev_u32_e32 v106, 51, v208
	v_subrev_u32_e32 v107, 50, v208
	v_subrev_u32_e32 v108, 53, v208
	v_subrev_u32_e32 v109, 52, v208
	v_subrev_u32_e32 v110, 55, v208
	v_subrev_u32_e32 v111, 54, v208
	v_cvt_f32_i32_e32 v112, v111
	v_cvt_f32_i32_e32 v110, v110
	v_cvt_f32_i32_e32 v111, v109
	v_cvt_f32_i32_e32 v108, v108
	v_cvt_f32_i32_e32 v109, v107
	v_cvt_f32_i32_e32 v106, v106
	v_cvt_f32_i32_e32 v107, v99
	v_cvt_f32_i32_e32 v113, v98
	v_cvt_f32_i32_e32 v114, v97
	v_cvt_f32_i32_e32 v115, v96
	v_cvt_f32_i32_e32 v105, v105
	v_cvt_f32_i32_e32 v104, v104
	v_cvt_f32_i32_e32 v96, v100
	v_cvt_f32_i32_e32 v98, v101
	v_cvt_f32_i32_e32 v99, v102
	v_cvt_f32_i32_e32 v100, v103
	v_and_b32_e32 v97, 0x7fffffff, v96
	v_and_b32_e32 v96, 0x7fffffff, v98
	v_and_b32_e32 v99, 0x7fffffff, v99
	v_and_b32_e32 v98, 0x7fffffff, v100
	v_and_b32_e32 v101, 0x7fffffff, v104
	v_and_b32_e32 v100, 0x7fffffff, v105
	v_and_b32_e32 v103, 0x7fffffff, v115
	v_and_b32_e32 v102, 0x7fffffff, v114
	v_and_b32_e32 v105, 0x7fffffff, v113
	v_and_b32_e32 v104, 0x7fffffff, v107
	v_and_b32_e32 v107, 0x7fffffff, v106
	v_and_b32_e32 v106, 0x7fffffff, v109
	v_and_b32_e32 v109, 0x7fffffff, v108
	v_and_b32_e32 v108, 0x7fffffff, v111
	v_and_b32_e32 v111, 0x7fffffff, v110
	v_and_b32_e32 v110, 0x7fffffff, v112
	v_pk_fma_f32 v[78:79], v[160:161], v[110:111], v[78:79] op_sel_hi:[0,1,1] neg_lo:[1,0,0] neg_hi:[1,0,0]
	v_pk_fma_f32 v[76:77], v[160:161], v[108:109], v[76:77] op_sel_hi:[0,1,1] neg_lo:[1,0,0] neg_hi:[1,0,0]
	v_pk_fma_f32 v[74:75], v[160:161], v[106:107], v[74:75] op_sel_hi:[0,1,1] neg_lo:[1,0,0] neg_hi:[1,0,0]
	v_pk_fma_f32 v[72:73], v[160:161], v[104:105], v[72:73] op_sel_hi:[0,1,1] neg_lo:[1,0,0] neg_hi:[1,0,0]
	v_pk_fma_f32 v[70:71], v[160:161], v[102:103], v[70:71] op_sel_hi:[0,1,1] neg_lo:[1,0,0] neg_hi:[1,0,0]
	v_pk_fma_f32 v[68:69], v[160:161], v[100:101], v[68:69] op_sel_hi:[0,1,1] neg_lo:[1,0,0] neg_hi:[1,0,0]
	v_pk_fma_f32 v[66:67], v[160:161], v[98:99], v[66:67] op_sel_hi:[0,1,1] neg_lo:[1,0,0] neg_hi:[1,0,0]
	v_pk_fma_f32 v[64:65], v[160:161], v[96:97], v[64:65] op_sel_hi:[0,1,1] neg_lo:[1,0,0] neg_hi:[1,0,0]
	s_waitcnt vmcnt(0) lgkmcnt(0)
	s_barrier
	v_add_f32_e32 v188, 0, v116
	s_cmp_lt_i32 s20, 4
	s_cbranch_scc1 .LBB0_305
	s_mov_b32 s4, 4
.Lrot301:
	s_mov_b32 s74, s4

.LBB0_303:
	v_add_f32_e32 v80, 0, v80
	v_add_f32_e32 v80, v81, v80
	v_add_f32_e32 v80, v82, v80
	v_add_f32_e32 v80, v83, v80
	v_add_f32_e32 v80, v84, v80
	v_add_f32_e32 v80, v85, v80
	v_add_f32_e32 v80, v86, v80
	v_add_f32_e32 v80, v87, v80
	v_add_f32_e32 v80, v88, v80
	v_add_f32_e32 v80, v89, v80
	v_add_f32_e32 v80, v90, v80
	v_add_f32_e32 v80, v91, v80
	v_add_f32_e32 v80, v92, v80
	v_add_f32_e32 v80, v93, v80
	v_add_f32_e32 v80, v94, v80
	v_add_f32_e32 v80, v95, v80
	v_add_f32_e32 v64, v64, v80
	v_add_f32_e32 v64, v65, v64
	v_add_f32_e32 v64, v66, v64
	v_add_f32_e32 v64, v67, v64
	v_add_f32_e32 v64, v68, v64
	v_add_f32_e32 v64, v69, v64
	v_add_f32_e32 v64, v70, v64
	v_add_f32_e32 v64, v71, v64
	v_add_f32_e32 v64, v72, v64
	v_add_f32_e32 v64, v73, v64
	v_add_f32_e32 v64, v74, v64
	v_add_f32_e32 v64, v75, v64
	v_add_f32_e32 v64, v76, v64
	v_add_f32_e32 v64, v77, v64
	v_add_f32_e32 v64, v78, v64
	v_add_f32_e32 v64, v79, v64
	s_lshl_b32 s4, s80, 14
	v_add_f32_e32 v192, v188, v64
	v_add_u32_e32 v64, s4, v170
	s_mov_b32 s5, m0
	s_mov_b32 m0, s78
	s_nop 0
	global_load_lds_dwordx4 v64, s[6:7]
	s_mov_b32 m0, s5
	v_add_u32_e32 v64, s4, v169
	s_mov_b32 s4, m0
	s_mov_b32 m0, s79
	s_nop 0
	global_load_lds_dwordx4 v64, s[6:7]
	s_mov_b32 m0, s4
	s_lshl_b32 s4, s80, 6
	s_cmp_lt_i32 s80, s68
	v_subrev_u32_e32 v64, s4, v159
	v_sub_u32_e32 v65, 0, v64
	s_cselect_b64 s[4:5], -1, 0
	v_cndmask_b32_e64 v64, v65, v64, s[4:5]
	v_cvt_f32_i32_e32 v64, v64
	v_cndmask_b32_e64 v67, v187, v186, s[4:5]
	v_cndmask_b32_e32 v128, 0, v67, vcc
	ds_read_b128 v[188:191], v171 offset:32768
	ds_read_b128 v[200:203], v171 offset:36864
	ds_read_b128 v[204:207], v174 offset:32768
	ds_read_b128 v[208:211], v174 offset:36864
	v_mul_f32_e64 v65, -v160, v64
	v_cvt_pk_bf16_f32 v65, v65, 0
	v_lshlrev_b32_e32 v65, 16, v65
	v_fma_f32 v64, -v160, v64, -v65
	v_cvt_pk_bf16_f32 v66, v64, 0
	v_lshlrev_b32_e32 v66, 16, v66
	v_sub_f32_e32 v64, v64, v66
	v_cvt_pk_bf16_f32 v65, v65, v66
	v_cvt_pk_bf16_f32 v64, v64, 0
	v_cndmask_b32_e32 v129, 0, v65, vcc
	v_cndmask_b32_e32 v130, 0, v64, vcc
	v_exp_f32_e32 v224, v112
	v_exp_f32_e32 v225, v113
	v_mfma_f32_32x32x16_bf16 v[80:95], v[152:155], v[128:131], 0
	v_add_f32_e32 v64, 0, v224
	v_add_f32_e32 v64, v225, v64
	v_exp_f32_e32 v226, v114
	v_exp_f32_e32 v227, v115
	v_add_f32_e32 v64, v226, v64
	v_add_f32_e32 v228, v227, v64
	v_mfma_f32_32x32x16_bf16 v[64:79], v[148:151], v[128:131], 0
	s_waitcnt lgkmcnt(3)
	v_mfma_f32_32x32x16_bf16 v[80:95], v[188:191], v[144:147], v[80:95]
	ds_read_b128 v[112:115], v172 offset:32768
	ds_read_b128 v[212:215], v172 offset:36864
	ds_read_b128 v[216:219], v173 offset:32768
	ds_read_b128 v[220:223], v173 offset:36864
	v_exp_f32_e32 v128, v116
	v_exp_f32_e32 v129, v117
	v_add_f32_e32 v116, v128, v228
	v_add_f32_e32 v130, v129, v116
	s_waitcnt lgkmcnt(6)
	v_mfma_f32_32x32x16_bf16 v[64:79], v[200:203], v[144:147], v[64:79]
	v_exp_f32_e32 v188, v118
	v_exp_f32_e32 v119, v119
	v_cvt_pk_bf16_f32 v116, v224, v225
	v_cvt_pk_bf16_f32 v117, v226, v227
	v_add_f32_e32 v118, v188, v130
	v_add_f32_e32 v130, v119, v118
	v_cvt_pk_bf16_f32 v118, v128, v129
	v_cvt_pk_bf16_f32 v119, v188, v119
	s_waitcnt lgkmcnt(5)
	v_mfma_f32_32x32x16_bf16 v[80:95], v[204:207], v[140:143], v[80:95]
	v_exp_f32_e32 v128, v120
	v_exp_f32_e32 v129, v121
	v_add_f32_e32 v120, v128, v130
	v_add_f32_e32 v120, v129, v120
	s_waitcnt lgkmcnt(4)
	v_mfma_f32_32x32x16_bf16 v[64:79], v[208:211], v[140:143], v[64:79]
	v_exp_f32_e32 v130, v122
	v_exp_f32_e32 v224, v123
	v_add_f32_e32 v120, v130, v120
	v_add_f32_e32 v225, v224, v120
	ds_read_b64_tr_b16 v[120:121], v175 offset:16384
	ds_read_b64_tr_b16 v[122:123], v176 offset:16384
	ds_read_b64_tr_b16 v[188:189], v177 offset:16384
	ds_read_b64_tr_b16 v[190:191], v178 offset:16384
	ds_read_b64_tr_b16 v[200:201], v179 offset:16384
	ds_read_b64_tr_b16 v[202:203], v182 offset:16384
	ds_read_b64_tr_b16 v[204:205], v183 offset:16384
	ds_read_b64_tr_b16 v[206:207], v184 offset:16384
	s_waitcnt lgkmcnt(11)
	v_mfma_f32_32x32x16_bf16 v[80:95], v[112:115], v[136:139], v[80:95]
	v_exp_f32_e32 v124, v124
	v_exp_f32_e32 v125, v125
	v_add_f32_e32 v112, v124, v225
	v_add_f32_e32 v114, v125, v112
	s_waitcnt lgkmcnt(10)
	v_mfma_f32_32x32x16_bf16 v[64:79], v[212:215], v[136:139], v[64:79]
	v_exp_f32_e32 v115, v126
	v_exp_f32_e32 v126, v127
	v_cvt_pk_bf16_f32 v112, v128, v129
	v_cvt_pk_bf16_f32 v113, v130, v224
	v_add_f32_e32 v114, v115, v114
	v_add_f32_e32 v128, v126, v114
	v_cvt_pk_bf16_f32 v114, v124, v125
	v_cvt_pk_bf16_f32 v115, v115, v126
	s_waitcnt lgkmcnt(9)
	v_mfma_f32_32x32x16_bf16 v[80:95], v[216:219], v[132:135], v[80:95]
	s_waitcnt lgkmcnt(8)
	v_mfma_f32_32x32x16_bf16 v[64:79], v[220:223], v[132:135], v[64:79]
	ds_read_b64_tr_b16 v[124:125], v175 offset:20480
	ds_read_b64_tr_b16 v[126:127], v176 offset:20480
	ds_read_b64_tr_b16 v[208:209], v177 offset:20480
	ds_read_b64_tr_b16 v[210:211], v178 offset:20480
	ds_read_b64_tr_b16 v[212:213], v179 offset:20480
	ds_read_b64_tr_b16 v[214:215], v182 offset:20480
	ds_read_b64_tr_b16 v[216:217], v183 offset:20480
	ds_read_b64_tr_b16 v[218:219], v184 offset:20480
	s_waitcnt lgkmcnt(14)
	v_mfma_f32_32x32x16_bf16 v[48:63], v[120:123], v[116:119], v[48:63]
	v_exp_f32_e32 v96, v96
	v_exp_f32_e32 v97, v97
	v_add_f32_e32 v120, v96, v128
	v_add_f32_e32 v120, v97, v120
	s_waitcnt lgkmcnt(12)
	v_mfma_f32_32x32x16_bf16 v[32:47], v[188:191], v[116:119], v[32:47]
	v_exp_f32_e32 v98, v98
	v_exp_f32_e32 v99, v99
	v_add_f32_e32 v120, v98, v120
	v_add_f32_e32 v120, v99, v120
	s_waitcnt lgkmcnt(10)
	v_mfma_f32_32x32x16_bf16 v[16:31], v[200:203], v[116:119], v[16:31]
	v_exp_f32_e32 v100, v100
	v_exp_f32_e32 v101, v101
	v_add_f32_e32 v120, v100, v120
	v_add_f32_e32 v120, v101, v120
	s_waitcnt lgkmcnt(8)
	v_mfma_f32_32x32x16_bf16 v[0:15], v[204:207], v[116:119], v[0:15]
	v_exp_f32_e32 v102, v102
	v_exp_f32_e32 v103, v103
	v_cvt_pk_bf16_f32 v96, v96, v97
	v_cvt_pk_bf16_f32 v97, v98, v99
	v_add_f32_e32 v98, v102, v120
	v_add_f32_e32 v128, v103, v98
	v_cvt_pk_bf16_f32 v98, v100, v101
	v_cvt_pk_bf16_f32 v99, v102, v103
	ds_read_b64_tr_b16 v[100:101], v175 offset:24576
	ds_read_b64_tr_b16 v[102:103], v176 offset:24576
	ds_read_b64_tr_b16 v[116:117], v177 offset:24576
	ds_read_b64_tr_b16 v[118:119], v178 offset:24576
	ds_read_b64_tr_b16 v[120:121], v179 offset:24576
	ds_read_b64_tr_b16 v[122:123], v182 offset:24576
	ds_read_b64_tr_b16 v[188:189], v183 offset:24576
	ds_read_b64_tr_b16 v[190:191], v184 offset:24576
	s_waitcnt lgkmcnt(14)
	v_mfma_f32_32x32x16_bf16 v[48:63], v[124:127], v[112:115], v[48:63]
	v_exp_f32_e32 v129, v104
	s_nop 0
	v_add_f32_e32 v104, v129, v128
	s_waitcnt lgkmcnt(12)
	v_mfma_f32_32x32x16_bf16 v[32:47], v[208:211], v[112:115], v[32:47]
	v_exp_f32_e32 v128, v105
	s_nop 0
	v_add_f32_e32 v104, v128, v104
	s_waitcnt lgkmcnt(10)
	v_mfma_f32_32x32x16_bf16 v[16:31], v[212:215], v[112:115], v[16:31]
	v_exp_f32_e32 v130, v106
	s_nop 0
	v_add_f32_e32 v104, v130, v104
	s_waitcnt lgkmcnt(8)
	v_mfma_f32_32x32x16_bf16 v[0:15], v[216:219], v[112:115], v[0:15]
	v_exp_f32_e32 v204, v107
	s_nop 0
	v_add_f32_e32 v205, v204, v104
	ds_read_b64_tr_b16 v[104:105], v175 offset:28672
	ds_read_b64_tr_b16 v[106:107], v176 offset:28672
	ds_read_b64_tr_b16 v[112:113], v177 offset:28672
	ds_read_b64_tr_b16 v[114:115], v178 offset:28672
	ds_read_b64_tr_b16 v[124:125], v179 offset:28672
	ds_read_b64_tr_b16 v[126:127], v182 offset:28672
	ds_read_b64_tr_b16 v[200:201], v183 offset:28672
	ds_read_b64_tr_b16 v[202:203], v184 offset:28672
	s_waitcnt lgkmcnt(14)
	v_mfma_f32_32x32x16_bf16 v[48:63], v[100:103], v[96:99], v[48:63]
	v_exp_f32_e32 v108, v108
	s_nop 0
	v_add_f32_e32 v100, v108, v205
	s_waitcnt lgkmcnt(12)
	v_mfma_f32_32x32x16_bf16 v[32:47], v[116:119], v[96:99], v[32:47]
	v_exp_f32_e32 v102, v109
	s_nop 0
	v_add_f32_e32 v100, v102, v100
	s_waitcnt lgkmcnt(10)
	v_mfma_f32_32x32x16_bf16 v[16:31], v[120:123], v[96:99], v[16:31]
	v_exp_f32_e32 v103, v110
	s_nop 0
	v_add_f32_e32 v109, v103, v100
	s_waitcnt lgkmcnt(8)
	v_mfma_f32_32x32x16_bf16 v[0:15], v[188:191], v[96:99], v[0:15]
	v_exp_f32_e32 v110, v111
	v_cvt_pk_bf16_f32 v100, v129, v128
	v_cvt_pk_bf16_f32 v101, v130, v204
	v_cvt_pk_bf16_f32 v102, v108, v102
	v_add_f32_e32 v108, v110, v109
	v_cvt_pk_bf16_f32 v103, v103, v110
	s_waitcnt lgkmcnt(6)
	s_nop 0
	v_mfma_f32_32x32x16_bf16 v[48:63], v[104:107], v[100:103], v[48:63]
	s_waitcnt lgkmcnt(4)
	v_mfma_f32_32x32x16_bf16 v[32:47], v[112:115], v[100:103], v[32:47]
	s_waitcnt lgkmcnt(2)
	v_mfma_f32_32x32x16_bf16 v[16:31], v[124:127], v[100:103], v[16:31]
	s_waitcnt lgkmcnt(0)
	v_mfma_f32_32x32x16_bf16 v[0:15], v[200:203], v[100:103], v[0:15]
	s_waitcnt vmcnt(0) lgkmcnt(0)
	s_barrier
	s_add_i32 s4, s74, 2
	s_add_i32 s5, s74, 1
	v_add_f32_e32 v188, v192, v108
	s_cmp_lt_i32 s5, s20
	s_cbranch_scc1 .Lrot301
